# v46 + MLA softmax row-max as a depth-4 max3 tree instead of a 16-long serial chain (bit-identical)
# speedup vs baseline: 1.0022x; 1.0022x over previous
.LBB0_516:
	s_add_i32 s4, s33, 0
	s_add_i32 s5, s34, 0
	s_add_i32 s5, s5, 0x10000
	s_waitcnt lgkmcnt(2)
	v_mfma_f32_32x32x16_bf16 v[68:83], v[170:173], v[100:103], 0
	v_mfma_f32_32x32x16_bf16 v[68:83], v[174:177], v[104:107], v[68:83]
	ds_read_b128 v[170:173], v215 offset:32768
	ds_read_b128 v[174:177], v216 offset:32768
	s_waitcnt lgkmcnt(2)
	v_mfma_f32_32x32x16_bf16 v[84:99], v[178:181], v[104:107], 0
	v_mfma_f32_32x32x16_bf16 v[84:99], v[182:185], v[100:103], v[84:99]
	ds_read_b128 v[178:181], v216 offset:40960
	ds_read_b128 v[182:185], v215 offset:40960
	s_waitcnt lgkmcnt(2)
	v_mfma_f32_32x32x16_bf16 v[84:99], v[170:173], v[108:111], v[84:99]
	v_mfma_f32_32x32x16_bf16 v[84:99], v[174:177], v[112:115], v[84:99]
	ds_read_b128 v[170:173], v217 offset:40960
	ds_read_b128 v[174:177], v218 offset:40960
	s_waitcnt lgkmcnt(2)
	v_mfma_f32_32x32x16_bf16 v[68:83], v[178:181], v[112:115], v[68:83]
	v_mfma_f32_32x32x16_bf16 v[68:83], v[182:185], v[108:111], v[68:83]
	ds_read_b128 v[178:181], v218 offset:32768
	ds_read_b128 v[182:185], v217 offset:32768
	s_waitcnt lgkmcnt(2)
	v_mfma_f32_32x32x16_bf16 v[68:83], v[170:173], v[116:119], v[68:83]
	v_mfma_f32_32x32x16_bf16 v[68:83], v[174:177], v[120:123], v[68:83]
	ds_read_b128 v[170:173], v219 offset:32768
	ds_read_b128 v[174:177], v220 offset:32768
	s_waitcnt lgkmcnt(2)
	v_mfma_f32_32x32x16_bf16 v[84:99], v[178:181], v[120:123], v[84:99]
	v_mfma_f32_32x32x16_bf16 v[84:99], v[182:185], v[116:119], v[84:99]
	ds_read_b128 v[178:181], v220 offset:40960
	ds_read_b128 v[182:185], v219 offset:40960
	s_waitcnt lgkmcnt(2)
	v_mfma_f32_32x32x16_bf16 v[84:99], v[170:173], v[124:127], v[84:99]
	v_mfma_f32_32x32x16_bf16 v[84:99], v[174:177], v[128:131], v[84:99]
	ds_read_b128 v[170:173], v221 offset:4096
	ds_read_b128 v[174:177], v222 offset:4096
	s_waitcnt lgkmcnt(2)
	v_mfma_f32_32x32x16_bf16 v[68:83], v[178:181], v[128:131], v[68:83]
	v_mfma_f32_32x32x16_bf16 v[68:83], v[182:185], v[124:127], v[68:83]
	ds_read_b128 v[178:181], v222 offset:0
	ds_read_b128 v[182:185], v221 offset:0
	s_waitcnt lgkmcnt(2)
	v_mfma_f32_32x32x16_bf16 v[68:83], v[170:173], v[186:189], v[68:83]
	v_mfma_f32_32x32x16_bf16 v[68:83], v[174:177], v[190:193], v[68:83]
	ds_read_b128 v[170:173], v223 offset:0
	ds_read_b128 v[174:177], v224 offset:0
	s_waitcnt lgkmcnt(2)
	v_mfma_f32_32x32x16_bf16 v[84:99], v[178:181], v[190:193], v[84:99]
	v_mfma_f32_32x32x16_bf16 v[84:99], v[182:185], v[186:189], v[84:99]
	ds_read_b128 v[178:181], v224 offset:4096
	ds_read_b128 v[182:185], v223 offset:4096
	s_waitcnt lgkmcnt(2)
	v_mfma_f32_32x32x16_bf16 v[84:99], v[170:173], v[194:197], v[84:99]
	v_mfma_f32_32x32x16_bf16 v[84:99], v[174:177], v[204:207], v[84:99]
	s_mov_b32 s4, 0x42ddb3d8
	s_waitcnt lgkmcnt(0)
	v_mfma_f32_32x32x16_bf16 v[68:83], v[178:181], v[204:207], v[68:83]
	v_mfma_f32_32x32x16_bf16 v[68:83], v[182:185], v[194:197], v[68:83]
	s_nop 10
	v_max3_f32 v226, v84, v85, v86
	v_max3_f32 v227, v87, v88, v89
	v_max3_f32 v228, v90, v91, v92
	v_max3_f32 v229, v93, v94, v95
	v_max3_f32 v230, v96, v97, v98
	v_max3_f32 v226, v226, v227, v228
	v_max3_f32 v229, v229, v230, v99
	s_nop 0
	v_max3_f32 v227, v68, v69, v70
	v_max3_f32 v228, v71, v72, v73
	v_max3_f32 v230, v74, v75, v76
	v_max3_f32 v231, v77, v78, v79
	v_max3_f32 v232, v80, v81, v82
	v_max3_f32 v227, v227, v228, v230
	v_max3_f32 v231, v231, v232, v83
	v_max3_f32 v226, v226, v229, v227
	v_max_f32_e32 v2, v226, v231
	v_mov_b32_e32 v145, v2
	s_nop 1
	v_permlane32_swap_b32_e32 v2, v145
	v_max_f32_e32 v2, v2, v145
	v_sub_f32_e32 v145, v2, v167
	v_cmp_ge_f32_e32 vcc, s4, v145
	s_cmp_eq_u64 vcc, exec
	s_cbranch_scc0 .Lmla_resc_slow
	v_mov_b32_e32 v2, 1.0
	s_mov_b64 s[4:5], -1

.LBB0_516b:
	s_add_i32 s4, s33, 0
	s_add_i32 s5, s34, 0
	s_add_i32 s5, s5, 0x10000
	s_waitcnt lgkmcnt(2)
	v_mfma_f32_32x32x16_bf16 v[68:83], v[170:173], v[100:103], 0
	v_mfma_f32_32x32x16_bf16 v[68:83], v[174:177], v[104:107], v[68:83]
	ds_read_b128 v[170:173], v215 offset:49152
	ds_read_b128 v[174:177], v216 offset:49152
	s_waitcnt lgkmcnt(2)
	v_mfma_f32_32x32x16_bf16 v[84:99], v[178:181], v[104:107], 0
	v_mfma_f32_32x32x16_bf16 v[84:99], v[182:185], v[100:103], v[84:99]
	ds_read_b128 v[178:181], v216 offset:57344
	ds_read_b128 v[182:185], v215 offset:57344
	s_waitcnt lgkmcnt(2)
	v_mfma_f32_32x32x16_bf16 v[84:99], v[170:173], v[108:111], v[84:99]
	v_mfma_f32_32x32x16_bf16 v[84:99], v[174:177], v[112:115], v[84:99]
	ds_read_b128 v[170:173], v217 offset:57344
	ds_read_b128 v[174:177], v218 offset:57344
	s_waitcnt lgkmcnt(2)
	v_mfma_f32_32x32x16_bf16 v[68:83], v[178:181], v[112:115], v[68:83]
	v_mfma_f32_32x32x16_bf16 v[68:83], v[182:185], v[108:111], v[68:83]
	ds_read_b128 v[178:181], v218 offset:49152
	ds_read_b128 v[182:185], v217 offset:49152
	s_waitcnt lgkmcnt(2)
	v_mfma_f32_32x32x16_bf16 v[68:83], v[170:173], v[116:119], v[68:83]
	v_mfma_f32_32x32x16_bf16 v[68:83], v[174:177], v[120:123], v[68:83]
	ds_read_b128 v[170:173], v219 offset:49152
	ds_read_b128 v[174:177], v220 offset:49152
	s_waitcnt lgkmcnt(2)
	v_mfma_f32_32x32x16_bf16 v[84:99], v[178:181], v[120:123], v[84:99]
	v_mfma_f32_32x32x16_bf16 v[84:99], v[182:185], v[116:119], v[84:99]
	ds_read_b128 v[178:181], v220 offset:57344
	ds_read_b128 v[182:185], v219 offset:57344
	s_waitcnt lgkmcnt(2)
	v_mfma_f32_32x32x16_bf16 v[84:99], v[170:173], v[124:127], v[84:99]
	v_mfma_f32_32x32x16_bf16 v[84:99], v[174:177], v[128:131], v[84:99]
	ds_read_b128 v[170:173], v221 offset:12288
	ds_read_b128 v[174:177], v222 offset:12288
	s_waitcnt lgkmcnt(2)
	v_mfma_f32_32x32x16_bf16 v[68:83], v[178:181], v[128:131], v[68:83]
	v_mfma_f32_32x32x16_bf16 v[68:83], v[182:185], v[124:127], v[68:83]
	ds_read_b128 v[178:181], v222 offset:8192
	ds_read_b128 v[182:185], v221 offset:8192
	s_waitcnt lgkmcnt(2)
	v_mfma_f32_32x32x16_bf16 v[68:83], v[170:173], v[186:189], v[68:83]
	v_mfma_f32_32x32x16_bf16 v[68:83], v[174:177], v[190:193], v[68:83]
	ds_read_b128 v[170:173], v223 offset:8192
	ds_read_b128 v[174:177], v224 offset:8192
	s_waitcnt lgkmcnt(2)
	v_mfma_f32_32x32x16_bf16 v[84:99], v[178:181], v[190:193], v[84:99]
	v_mfma_f32_32x32x16_bf16 v[84:99], v[182:185], v[186:189], v[84:99]
	ds_read_b128 v[178:181], v224 offset:12288
	ds_read_b128 v[182:185], v223 offset:12288
	s_waitcnt lgkmcnt(2)
	v_mfma_f32_32x32x16_bf16 v[84:99], v[170:173], v[194:197], v[84:99]
	v_mfma_f32_32x32x16_bf16 v[84:99], v[174:177], v[204:207], v[84:99]
	s_mov_b32 s4, 0x42ddb3d8
	s_waitcnt lgkmcnt(0)
	v_mfma_f32_32x32x16_bf16 v[68:83], v[178:181], v[204:207], v[68:83]
	v_mfma_f32_32x32x16_bf16 v[68:83], v[182:185], v[194:197], v[68:83]
	s_nop 10
	v_max3_f32 v226, v84, v85, v86
	v_max3_f32 v227, v87, v88, v89
	v_max3_f32 v228, v90, v91, v92
	v_max3_f32 v229, v93, v94, v95
	v_max3_f32 v230, v96, v97, v98
	v_max3_f32 v226, v226, v227, v228
	v_max3_f32 v229, v229, v230, v99
	s_nop 0
	v_max3_f32 v227, v68, v69, v70
	v_max3_f32 v228, v71, v72, v73
	v_max3_f32 v230, v74, v75, v76
	v_max3_f32 v231, v77, v78, v79
	v_max3_f32 v232, v80, v81, v82
	v_max3_f32 v227, v227, v228, v230
	v_max3_f32 v231, v231, v232, v83
	v_max3_f32 v226, v226, v229, v227
	v_max_f32_e32 v2, v226, v231
	v_mov_b32_e32 v145, v2
	s_nop 1
	v_permlane32_swap_b32_e32 v2, v145
	v_max_f32_e32 v2, v2, v145
	v_sub_f32_e32 v145, v2, v167
	v_cmp_ge_f32_e32 vcc, s4, v145
	s_cmp_eq_u64 vcc, exec
	s_cbranch_scc0 .Lmla_resc_slowb
	v_mov_b32_e32 v2, 1.0
	s_mov_b64 s[4:5], -1
